# lru_final token loop: issue the 96 loads of a 32-token batch before computing (was one round trip per token)
# speedup vs baseline: 1.0180x; 1.0180x over previous
.LBB0_1328:
	s_add_i32 s10, s34, s1
	s_lshl_b32 s12, s10, 10
	s_add_i32 s12, s12, 0x1000
	s_lshl_b32 s13, s10, 11
	s_add_i32 s13, s13, 0x1000
	s_add_u32 s62, s22, s12
	s_addc_u32 s63, s23, 0
	s_add_u32 s64, s20, s12
	s_addc_u32 s65, s21, 0
	s_add_u32 s66, s18, s12
	s_addc_u32 s67, s19, 0
	s_add_u32 s70, s36, s13
	s_addc_u32 s71, s37, 0
	s_add_i32 s1, s1, 32
	global_load_ushort v94, v4, s[62:63] offset:-4096
	global_load_ushort v126, v4, s[64:65] offset:-4096
	global_load_ushort v158, v4, s[66:67] offset:-4096
	global_load_ushort v95, v4, s[62:63] offset:-3072
	global_load_ushort v127, v4, s[64:65] offset:-3072
	global_load_ushort v159, v4, s[66:67] offset:-3072
	global_load_ushort v96, v4, s[62:63] offset:-2048
	global_load_ushort v128, v4, s[64:65] offset:-2048
	global_load_ushort v160, v4, s[66:67] offset:-2048
	global_load_ushort v97, v4, s[62:63] offset:-1024
	global_load_ushort v129, v4, s[64:65] offset:-1024
	global_load_ushort v161, v4, s[66:67] offset:-1024
	global_load_ushort v98, v4, s[62:63]
	global_load_ushort v130, v4, s[64:65]
	global_load_ushort v162, v4, s[66:67]
	global_load_ushort v99, v4, s[62:63] offset:1024
	global_load_ushort v131, v4, s[64:65] offset:1024
	global_load_ushort v163, v4, s[66:67] offset:1024
	global_load_ushort v100, v4, s[62:63] offset:2048
	global_load_ushort v132, v4, s[64:65] offset:2048
	global_load_ushort v164, v4, s[66:67] offset:2048
	global_load_ushort v101, v4, s[62:63] offset:3072
	global_load_ushort v133, v4, s[64:65] offset:3072
	global_load_ushort v165, v4, s[66:67] offset:3072
	s_add_u32 s62, s62, 0x2000
	s_addc_u32 s63, s63, 0
	s_add_u32 s64, s64, 0x2000
	s_addc_u32 s65, s65, 0
	s_add_u32 s66, s66, 0x2000
	s_addc_u32 s67, s67, 0
	global_load_ushort v102, v4, s[62:63] offset:-4096
	global_load_ushort v134, v4, s[64:65] offset:-4096
	global_load_ushort v166, v4, s[66:67] offset:-4096
	global_load_ushort v103, v4, s[62:63] offset:-3072
	global_load_ushort v135, v4, s[64:65] offset:-3072
	global_load_ushort v167, v4, s[66:67] offset:-3072
	global_load_ushort v104, v4, s[62:63] offset:-2048
	global_load_ushort v136, v4, s[64:65] offset:-2048
	global_load_ushort v168, v4, s[66:67] offset:-2048
	global_load_ushort v105, v4, s[62:63] offset:-1024
	global_load_ushort v137, v4, s[64:65] offset:-1024
	global_load_ushort v169, v4, s[66:67] offset:-1024
	global_load_ushort v106, v4, s[62:63]
	global_load_ushort v138, v4, s[64:65]
	global_load_ushort v170, v4, s[66:67]
	global_load_ushort v107, v4, s[62:63] offset:1024
	global_load_ushort v139, v4, s[64:65] offset:1024
	global_load_ushort v171, v4, s[66:67] offset:1024
	global_load_ushort v108, v4, s[62:63] offset:2048
	global_load_ushort v140, v4, s[64:65] offset:2048
	global_load_ushort v172, v4, s[66:67] offset:2048
	global_load_ushort v109, v4, s[62:63] offset:3072
	global_load_ushort v141, v4, s[64:65] offset:3072
	global_load_ushort v173, v4, s[66:67] offset:3072
	s_add_u32 s62, s62, 0x2000
	s_addc_u32 s63, s63, 0
	s_add_u32 s64, s64, 0x2000
	s_addc_u32 s65, s65, 0
	s_add_u32 s66, s66, 0x2000
	s_addc_u32 s67, s67, 0
	global_load_ushort v110, v4, s[62:63] offset:-4096
	global_load_ushort v142, v4, s[64:65] offset:-4096
	global_load_ushort v174, v4, s[66:67] offset:-4096
	global_load_ushort v111, v4, s[62:63] offset:-3072
	global_load_ushort v143, v4, s[64:65] offset:-3072
	global_load_ushort v175, v4, s[66:67] offset:-3072
	global_load_ushort v112, v4, s[62:63] offset:-2048
	global_load_ushort v144, v4, s[64:65] offset:-2048
	global_load_ushort v176, v4, s[66:67] offset:-2048
	global_load_ushort v113, v4, s[62:63] offset:-1024
	global_load_ushort v145, v4, s[64:65] offset:-1024
	global_load_ushort v177, v4, s[66:67] offset:-1024
	global_load_ushort v114, v4, s[62:63]
	global_load_ushort v146, v4, s[64:65]
	global_load_ushort v178, v4, s[66:67]
	global_load_ushort v115, v4, s[62:63] offset:1024
	global_load_ushort v147, v4, s[64:65] offset:1024
	global_load_ushort v179, v4, s[66:67] offset:1024
	global_load_ushort v116, v4, s[62:63] offset:2048
	global_load_ushort v148, v4, s[64:65] offset:2048
	global_load_ushort v180, v4, s[66:67] offset:2048
	global_load_ushort v117, v4, s[62:63] offset:3072
	global_load_ushort v149, v4, s[64:65] offset:3072
	global_load_ushort v181, v4, s[66:67] offset:3072
	s_add_u32 s62, s62, 0x2000
	s_addc_u32 s63, s63, 0
	s_add_u32 s64, s64, 0x2000
	s_addc_u32 s65, s65, 0
	s_add_u32 s66, s66, 0x2000
	s_addc_u32 s67, s67, 0
	global_load_ushort v118, v4, s[62:63] offset:-4096
	global_load_ushort v150, v4, s[64:65] offset:-4096
	global_load_ushort v182, v4, s[66:67] offset:-4096
	global_load_ushort v119, v4, s[62:63] offset:-3072
	global_load_ushort v151, v4, s[64:65] offset:-3072
	global_load_ushort v183, v4, s[66:67] offset:-3072
	global_load_ushort v120, v4, s[62:63] offset:-2048
	global_load_ushort v152, v4, s[64:65] offset:-2048
	global_load_ushort v184, v4, s[66:67] offset:-2048
	global_load_ushort v121, v4, s[62:63] offset:-1024
	global_load_ushort v153, v4, s[64:65] offset:-1024
	global_load_ushort v185, v4, s[66:67] offset:-1024
	global_load_ushort v122, v4, s[62:63]
	global_load_ushort v154, v4, s[64:65]
	global_load_ushort v218, v4, s[66:67]
	global_load_ushort v123, v4, s[62:63] offset:1024
	global_load_ushort v155, v4, s[64:65] offset:1024
	global_load_ushort v219, v4, s[66:67] offset:1024
	global_load_ushort v124, v4, s[62:63] offset:2048
	global_load_ushort v156, v4, s[64:65] offset:2048
	global_load_ushort v220, v4, s[66:67] offset:2048
	global_load_ushort v125, v4, s[62:63] offset:3072
	global_load_ushort v157, v4, s[64:65] offset:3072
	global_load_ushort v221, v4, s[66:67] offset:3072
	s_waitcnt vmcnt(63)
	v_lshlrev_b32_e32 v94, 16, v94
	v_lshlrev_b32_e32 v126, 16, v126
	v_lshlrev_b32_e32 v158, 16, v158
	v_fmac_f32_e32 v94, v10, v126
	v_mul_f32_e32 v94, v94, v158
	v_cvt_pk_bf16_f32 v94, v94, s0
	global_store_short v4, v94, s[70:71] offset:-4096
	s_waitcnt vmcnt(63)
	v_lshlrev_b32_e32 v95, 16, v95
	v_lshlrev_b32_e32 v127, 16, v127
	v_lshlrev_b32_e32 v159, 16, v159
	v_fmac_f32_e32 v95, v10, v127
	v_mul_f32_e32 v95, v95, v159
	v_cvt_pk_bf16_f32 v95, v95, s0
	global_store_short v4, v95, s[70:71] offset:-2048
	s_waitcnt vmcnt(63)
	v_lshlrev_b32_e32 v96, 16, v96
	v_lshlrev_b32_e32 v128, 16, v128
	v_lshlrev_b32_e32 v160, 16, v160
	v_fmac_f32_e32 v96, v10, v128
	v_mul_f32_e32 v96, v96, v160
	v_cvt_pk_bf16_f32 v96, v96, s0
	global_store_short v4, v96, s[70:71]
	s_waitcnt vmcnt(63)
	v_lshlrev_b32_e32 v97, 16, v97
	v_lshlrev_b32_e32 v129, 16, v129
	v_lshlrev_b32_e32 v161, 16, v161
	v_fmac_f32_e32 v97, v10, v129
	v_mul_f32_e32 v97, v97, v161
	v_cvt_pk_bf16_f32 v97, v97, s0
	global_store_short v4, v97, s[70:71] offset:2048
	s_add_u32 s70, s70, 0x2000
	s_addc_u32 s71, s71, 0
	s_waitcnt vmcnt(63)
	v_lshlrev_b32_e32 v98, 16, v98
	v_lshlrev_b32_e32 v130, 16, v130
	v_lshlrev_b32_e32 v162, 16, v162
	v_fmac_f32_e32 v98, v10, v130
	v_mul_f32_e32 v98, v98, v162
	v_cvt_pk_bf16_f32 v98, v98, s0
	global_store_short v4, v98, s[70:71] offset:-4096
	s_waitcnt vmcnt(63)
	v_lshlrev_b32_e32 v99, 16, v99
	v_lshlrev_b32_e32 v131, 16, v131
	v_lshlrev_b32_e32 v163, 16, v163
	v_fmac_f32_e32 v99, v10, v131
	v_mul_f32_e32 v99, v99, v163
	v_cvt_pk_bf16_f32 v99, v99, s0
	global_store_short v4, v99, s[70:71] offset:-2048
	s_waitcnt vmcnt(63)
	v_lshlrev_b32_e32 v100, 16, v100
	v_lshlrev_b32_e32 v132, 16, v132
	v_lshlrev_b32_e32 v164, 16, v164
	v_fmac_f32_e32 v100, v10, v132
	v_mul_f32_e32 v100, v100, v164
	v_cvt_pk_bf16_f32 v100, v100, s0
	global_store_short v4, v100, s[70:71]
	s_waitcnt vmcnt(63)
	v_lshlrev_b32_e32 v101, 16, v101
	v_lshlrev_b32_e32 v133, 16, v133
	v_lshlrev_b32_e32 v165, 16, v165
	v_fmac_f32_e32 v101, v10, v133
	v_mul_f32_e32 v101, v101, v165
	v_cvt_pk_bf16_f32 v101, v101, s0
	global_store_short v4, v101, s[70:71] offset:2048
	s_add_u32 s70, s70, 0x2000
	s_addc_u32 s71, s71, 0
	s_waitcnt vmcnt(63)
	v_lshlrev_b32_e32 v102, 16, v102
	v_lshlrev_b32_e32 v134, 16, v134
	v_lshlrev_b32_e32 v166, 16, v166
	v_fmac_f32_e32 v102, v10, v134
	v_mul_f32_e32 v102, v102, v166
	v_cvt_pk_bf16_f32 v102, v102, s0
	global_store_short v4, v102, s[70:71] offset:-4096
	s_waitcnt vmcnt(63)
	v_lshlrev_b32_e32 v103, 16, v103
	v_lshlrev_b32_e32 v135, 16, v135
	v_lshlrev_b32_e32 v167, 16, v167
	v_fmac_f32_e32 v103, v10, v135
	v_mul_f32_e32 v103, v103, v167
	v_cvt_pk_bf16_f32 v103, v103, s0
	global_store_short v4, v103, s[70:71] offset:-2048
	s_waitcnt vmcnt(63)
	v_lshlrev_b32_e32 v104, 16, v104
	v_lshlrev_b32_e32 v136, 16, v136
	v_lshlrev_b32_e32 v168, 16, v168
	v_fmac_f32_e32 v104, v10, v136
	v_mul_f32_e32 v104, v104, v168
	v_cvt_pk_bf16_f32 v104, v104, s0
	global_store_short v4, v104, s[70:71]
	s_waitcnt vmcnt(63)
	v_lshlrev_b32_e32 v105, 16, v105
	v_lshlrev_b32_e32 v137, 16, v137
	v_lshlrev_b32_e32 v169, 16, v169
	v_fmac_f32_e32 v105, v10, v137
	v_mul_f32_e32 v105, v105, v169
	v_cvt_pk_bf16_f32 v105, v105, s0
	global_store_short v4, v105, s[70:71] offset:2048
	s_add_u32 s70, s70, 0x2000
	s_addc_u32 s71, s71, 0
	s_waitcnt vmcnt(63)
	v_lshlrev_b32_e32 v106, 16, v106
	v_lshlrev_b32_e32 v138, 16, v138
	v_lshlrev_b32_e32 v170, 16, v170
	v_fmac_f32_e32 v106, v10, v138
	v_mul_f32_e32 v106, v106, v170
	v_cvt_pk_bf16_f32 v106, v106, s0
	global_store_short v4, v106, s[70:71] offset:-4096
	s_waitcnt vmcnt(63)
	v_lshlrev_b32_e32 v107, 16, v107
	v_lshlrev_b32_e32 v139, 16, v139
	v_lshlrev_b32_e32 v171, 16, v171
	v_fmac_f32_e32 v107, v10, v139
	v_mul_f32_e32 v107, v107, v171
	v_cvt_pk_bf16_f32 v107, v107, s0
	global_store_short v4, v107, s[70:71] offset:-2048
	s_waitcnt vmcnt(63)
	v_lshlrev_b32_e32 v108, 16, v108
	v_lshlrev_b32_e32 v140, 16, v140
	v_lshlrev_b32_e32 v172, 16, v172
	v_fmac_f32_e32 v108, v10, v140
	v_mul_f32_e32 v108, v108, v172
	v_cvt_pk_bf16_f32 v108, v108, s0
	global_store_short v4, v108, s[70:71]
	s_waitcnt vmcnt(63)
	v_lshlrev_b32_e32 v109, 16, v109
	v_lshlrev_b32_e32 v141, 16, v141
	v_lshlrev_b32_e32 v173, 16, v173
	v_fmac_f32_e32 v109, v10, v141
	v_mul_f32_e32 v109, v109, v173
	v_cvt_pk_bf16_f32 v109, v109, s0
	global_store_short v4, v109, s[70:71] offset:2048
	s_add_u32 s70, s70, 0x2000
	s_addc_u32 s71, s71, 0
	s_waitcnt vmcnt(61)
	v_lshlrev_b32_e32 v110, 16, v110
	v_lshlrev_b32_e32 v142, 16, v142
	v_lshlrev_b32_e32 v174, 16, v174
	v_fmac_f32_e32 v110, v10, v142
	v_mul_f32_e32 v110, v110, v174
	v_cvt_pk_bf16_f32 v110, v110, s0
	global_store_short v4, v110, s[70:71] offset:-4096
	s_waitcnt vmcnt(59)
	v_lshlrev_b32_e32 v111, 16, v111
	v_lshlrev_b32_e32 v143, 16, v143
	v_lshlrev_b32_e32 v175, 16, v175
	v_fmac_f32_e32 v111, v10, v143
	v_mul_f32_e32 v111, v111, v175
	v_cvt_pk_bf16_f32 v111, v111, s0
	global_store_short v4, v111, s[70:71] offset:-2048
	s_waitcnt vmcnt(57)
	v_lshlrev_b32_e32 v112, 16, v112
	v_lshlrev_b32_e32 v144, 16, v144
	v_lshlrev_b32_e32 v176, 16, v176
	v_fmac_f32_e32 v112, v10, v144
	v_mul_f32_e32 v112, v112, v176
	v_cvt_pk_bf16_f32 v112, v112, s0
	global_store_short v4, v112, s[70:71]
	s_waitcnt vmcnt(55)
	v_lshlrev_b32_e32 v113, 16, v113
	v_lshlrev_b32_e32 v145, 16, v145
	v_lshlrev_b32_e32 v177, 16, v177
	v_fmac_f32_e32 v113, v10, v145
	v_mul_f32_e32 v113, v113, v177
	v_cvt_pk_bf16_f32 v113, v113, s0
	global_store_short v4, v113, s[70:71] offset:2048
	s_add_u32 s70, s70, 0x2000
	s_addc_u32 s71, s71, 0
	s_waitcnt vmcnt(53)
	v_lshlrev_b32_e32 v114, 16, v114
	v_lshlrev_b32_e32 v146, 16, v146
	v_lshlrev_b32_e32 v178, 16, v178
	v_fmac_f32_e32 v114, v10, v146
	v_mul_f32_e32 v114, v114, v178
	v_cvt_pk_bf16_f32 v114, v114, s0
	global_store_short v4, v114, s[70:71] offset:-4096
	s_waitcnt vmcnt(51)
	v_lshlrev_b32_e32 v115, 16, v115
	v_lshlrev_b32_e32 v147, 16, v147
	v_lshlrev_b32_e32 v179, 16, v179
	v_fmac_f32_e32 v115, v10, v147
	v_mul_f32_e32 v115, v115, v179
	v_cvt_pk_bf16_f32 v115, v115, s0
	global_store_short v4, v115, s[70:71] offset:-2048
	s_waitcnt vmcnt(49)
	v_lshlrev_b32_e32 v116, 16, v116
	v_lshlrev_b32_e32 v148, 16, v148
	v_lshlrev_b32_e32 v180, 16, v180
	v_fmac_f32_e32 v116, v10, v148
	v_mul_f32_e32 v116, v116, v180
	v_cvt_pk_bf16_f32 v116, v116, s0
	global_store_short v4, v116, s[70:71]
	s_waitcnt vmcnt(47)
	v_lshlrev_b32_e32 v117, 16, v117
	v_lshlrev_b32_e32 v149, 16, v149
	v_lshlrev_b32_e32 v181, 16, v181
	v_fmac_f32_e32 v117, v10, v149
	v_mul_f32_e32 v117, v117, v181
	v_cvt_pk_bf16_f32 v117, v117, s0
	global_store_short v4, v117, s[70:71] offset:2048
	s_add_u32 s70, s70, 0x2000
	s_addc_u32 s71, s71, 0
	s_waitcnt vmcnt(45)
	v_lshlrev_b32_e32 v118, 16, v118
	v_lshlrev_b32_e32 v150, 16, v150
	v_lshlrev_b32_e32 v182, 16, v182
	v_fmac_f32_e32 v118, v10, v150
	v_mul_f32_e32 v118, v118, v182
	v_cvt_pk_bf16_f32 v118, v118, s0
	global_store_short v4, v118, s[70:71] offset:-4096
	s_waitcnt vmcnt(43)
	v_lshlrev_b32_e32 v119, 16, v119
	v_lshlrev_b32_e32 v151, 16, v151
	v_lshlrev_b32_e32 v183, 16, v183
	v_fmac_f32_e32 v119, v10, v151
	v_mul_f32_e32 v119, v119, v183
	v_cvt_pk_bf16_f32 v119, v119, s0
	global_store_short v4, v119, s[70:71] offset:-2048
	s_waitcnt vmcnt(41)
	v_lshlrev_b32_e32 v120, 16, v120
	v_lshlrev_b32_e32 v152, 16, v152
	v_lshlrev_b32_e32 v184, 16, v184
	v_fmac_f32_e32 v120, v10, v152
	v_mul_f32_e32 v120, v120, v184
	v_cvt_pk_bf16_f32 v120, v120, s0
	global_store_short v4, v120, s[70:71]
	s_waitcnt vmcnt(39)
	v_lshlrev_b32_e32 v121, 16, v121
	v_lshlrev_b32_e32 v153, 16, v153
	v_lshlrev_b32_e32 v185, 16, v185
	v_fmac_f32_e32 v121, v10, v153
	v_mul_f32_e32 v121, v121, v185
	v_cvt_pk_bf16_f32 v121, v121, s0
	global_store_short v4, v121, s[70:71] offset:2048
	s_add_u32 s70, s70, 0x2000
	s_addc_u32 s71, s71, 0
	s_waitcnt vmcnt(37)
	v_lshlrev_b32_e32 v122, 16, v122
	v_lshlrev_b32_e32 v154, 16, v154
	v_lshlrev_b32_e32 v218, 16, v218
	v_fmac_f32_e32 v122, v10, v154
	v_mul_f32_e32 v122, v122, v218
	v_cvt_pk_bf16_f32 v122, v122, s0
	global_store_short v4, v122, s[70:71] offset:-4096
	s_waitcnt vmcnt(35)
	v_lshlrev_b32_e32 v123, 16, v123
	v_lshlrev_b32_e32 v155, 16, v155
	v_lshlrev_b32_e32 v219, 16, v219
	v_fmac_f32_e32 v123, v10, v155
	v_mul_f32_e32 v123, v123, v219
	v_cvt_pk_bf16_f32 v123, v123, s0
	global_store_short v4, v123, s[70:71] offset:-2048
	s_waitcnt vmcnt(33)
	v_lshlrev_b32_e32 v124, 16, v124
	v_lshlrev_b32_e32 v156, 16, v156
	v_lshlrev_b32_e32 v220, 16, v220
	v_fmac_f32_e32 v124, v10, v156
	v_mul_f32_e32 v124, v124, v220
	v_cvt_pk_bf16_f32 v124, v124, s0
	global_store_short v4, v124, s[70:71]
	s_waitcnt vmcnt(31)
	v_lshlrev_b32_e32 v125, 16, v125
	v_lshlrev_b32_e32 v157, 16, v157
	v_lshlrev_b32_e32 v221, 16, v221
	v_fmac_f32_e32 v125, v10, v157
	v_mul_f32_e32 v125, v125, v221
	v_cvt_pk_bf16_f32 v125, v125, s0
	global_store_short v4, v125, s[70:71] offset:2048
	s_cmp_eq_u32 s69, s1
	s_cbranch_scc0 .LBB0_1328
	s_cmpk_eq_i32 s27, 0x7f
	s_cselect_b64 s[12:13], -1, 0
	s_or_b64 s[6:7], s[6:7], s[12:13]
	s_and_b64 vcc, exec, s[6:7]
	s_cbranch_vccz .LBB0_1335
	s_add_i32 s1, s69, s34
	v_lshlrev_b64 v[6:7], 2, v[2:3]
	s_add_i32 s10, s1, -3
	s_mov_b64 s[6:7], -1
	s_andn2_b64 vcc, exec, s[4:5]
	v_lshl_add_u64 v[4:5], s[16:17], 0, v[6:7]
	s_cbranch_vccnz .LBB0_1332
	s_lshl_b64 s[4:5], s[10:11], 11
	v_lshl_add_u64 v[8:9], v[4:5], 0, s[4:5]
	global_load_dword v11, v[8:9], off
	s_mul_i32 s4, s0, 3
	s_mov_b32 s5, s11
	s_lshl_b64 s[12:13], s[4:5], 11
	s_add_u32 s12, s84, s12
	s_addc_u32 s13, s85, s13
	v_lshl_add_u64 v[8:9], s[12:13], 0, v[6:7]
	s_mov_b32 s1, 0x10102000
	s_mov_b32 s7, s11
	s_add_i32 s6, s10, 1
	v_add_co_u32_e32 v8, vcc, s1, v8
	s_lshl_b64 s[6:7], s[6:7], 11
	s_nop 0
	v_addc_co_u32_e32 v9, vcc, 0, v9, vcc
	v_lshl_add_u64 v[12:13], v[4:5], 0, s[6:7]
	s_mov_b32 s7, s11
	s_add_i32 s6, s4, 1
	s_lshl_b64 s[6:7], s[6:7], 11
	s_add_u32 s6, s84, s6
	s_addc_u32 s7, s85, s7
	s_mov_b32 s13, s11
	s_add_i32 s12, s10, 2
	s_add_i32 s4, s4, 2
	s_waitcnt vmcnt(0)
	global_store_dword v[8:9], v11, off
	global_load_dword v11, v[12:13], off
	v_lshl_add_u64 v[12:13], s[6:7], 0, v[6:7]
	s_lshl_b64 s[6:7], s[12:13], 11
	v_add_co_u32_e32 v12, vcc, 0x10102000, v12
	v_lshl_add_u64 v[8:9], v[4:5], 0, s[6:7]
	s_nop 0
	v_addc_co_u32_e32 v13, vcc, 0, v13, vcc
	s_mov_b64 s[6:7], 0
	s_waitcnt vmcnt(0)
	global_store_dword v[12:13], v11, off
